# v65 + cross-phase L2 warm-up: waves 1-7 touch the first four K-tiles of the next phase's weight tile while waiting at the grid barrier (merge, W_o, gate phases)
# baseline (speedup 1.0000x reference)
; __device__ __forceinline__ void xcd_barrier(const XcdBarrier& b, bool local = false) {
;     asm volatile("s_waitcnt vmcnt(0)" ::: "memory");
;     __syncthreads();
;     if (threadIdx.x == 0) {
; __global__ void __launch_bounds__(512, 2) fwd_megakernel(Args a) {
;     ...
;             pg8::Gemm g{Y, (const bf16_t*)(ws + WS_WB + l * SZ_WB), YW, YW, YW, MTOK / 256, DM / 256, 0, lx, lr};
;             EpiMerge E{PROJ, MG};
;             pg8::gemm_phase<EpiMerge>(lds, g, E);
.LBB0_583:
	s_or_b64 exec, exec, s[40:41]
	s_and_b64 vcc, exec, s[76:77]
	s_cbranch_vccz .Lwu0_x
	v_readfirstlane_b32 s98, v188
	s_cmp_lt_u32 s98, 64
	s_cbranch_scc1 .Lwu0_x
	v_readlane_b32 s98, v251, 32
	v_readlane_b32 s99, v251, 33
	v_readlane_b32 vcc_lo, v251, 53
	v_mov_b32_e32 v2, 0x180000
	v_mov_b32_e32 v3, 0xc00000
	s_nop 0
	v_mul_lo_u32 v2, v2, vcc_lo
	v_mul_lo_u32 v3, v3, s78
	v_add_u32_e32 v2, v2, v3
	v_subrev_u32_e32 v4, 64, v188
	v_add_u32_e32 v5, 0, v4
	v_min_u32_e32 v5, 0x3ff, v5
	v_lshrrev_b32_e32 v6, 2, v5
	v_and_b32_e32 v5, 3, v5
	v_mul_u32_u24_e32 v6, 0x1800, v6
	v_lshl_add_u32 v6, v5, 7, v6
	v_add_u32_e32 v6, v6, v2
	global_load_dword v254, v6, s[98:99]
	v_add_u32_e32 v5, 448, v4
	v_min_u32_e32 v5, 0x3ff, v5
	v_lshrrev_b32_e32 v6, 2, v5
	v_and_b32_e32 v5, 3, v5
	v_mul_u32_u24_e32 v6, 0x1800, v6
	v_lshl_add_u32 v6, v5, 7, v6
	v_add_u32_e32 v6, v6, v2
	global_load_dword v254, v6, s[98:99]
	v_add_u32_e32 v5, 896, v4
	v_min_u32_e32 v5, 0x3ff, v5
	v_lshrrev_b32_e32 v6, 2, v5
	v_and_b32_e32 v5, 3, v5
	v_mul_u32_u24_e32 v6, 0x1800, v6
	v_lshl_add_u32 v6, v5, 7, v6
	v_add_u32_e32 v6, v6, v2
	global_load_dword v254, v6, s[98:99]
.Lwu0_x:
	s_waitcnt lgkmcnt(0)
	s_barrier

; __device__ __forceinline__ void xcd_barrier(const XcdBarrier& b, bool local = false) {
;     asm volatile("s_waitcnt vmcnt(0)" ::: "memory");
;     __syncthreads();
;     if (threadIdx.x == 0) {
; __global__ void __launch_bounds__(512, 2) fwd_megakernel(Args a) {
;     ...
;             pg8::Gemm g{MG, (const bf16_t*)(ws + WS_WO + l * SZ_WO), DM, DM, DM, MTOK / 256, DM / 256, 0, lx, lr};
;             EpiWo E{(const float*)nullptr, hb0, hb1};
;             pg8::gemm_phase<EpiWo>(lds, g, E);
.LBB0_682:
	s_or_b64 exec, exec, s[40:41]
	s_and_b64 vcc, exec, s[76:77]
	s_cbranch_vccz .Lwu1_x
	v_readfirstlane_b32 s98, v188
	s_cmp_lt_u32 s98, 64
	s_cbranch_scc1 .Lwu1_x
	v_readlane_b32 s98, v251, 36
	v_readlane_b32 s99, v251, 37
	v_readlane_b32 vcc_lo, v251, 53
	v_mov_b32_e32 v2, 0x100000
	v_mov_b32_e32 v3, 0x800000
	s_nop 0
	v_mul_lo_u32 v2, v2, vcc_lo
	v_mul_lo_u32 v3, v3, s78
	v_add_u32_e32 v2, v2, v3
	v_subrev_u32_e32 v4, 64, v188
	v_add_u32_e32 v5, 0, v4
	v_min_u32_e32 v5, 0x3ff, v5
	v_lshrrev_b32_e32 v6, 2, v5
	v_and_b32_e32 v5, 3, v5
	v_mul_u32_u24_e32 v6, 0x1000, v6
	v_lshl_add_u32 v6, v5, 7, v6
	v_add_u32_e32 v6, v6, v2
	global_load_dword v254, v6, s[98:99]
	v_add_u32_e32 v5, 448, v4
	v_min_u32_e32 v5, 0x3ff, v5
	v_lshrrev_b32_e32 v6, 2, v5
	v_and_b32_e32 v5, 3, v5
	v_mul_u32_u24_e32 v6, 0x1000, v6
	v_lshl_add_u32 v6, v5, 7, v6
	v_add_u32_e32 v6, v6, v2
	global_load_dword v254, v6, s[98:99]
	v_add_u32_e32 v5, 896, v4
	v_min_u32_e32 v5, 0x3ff, v5
	v_lshrrev_b32_e32 v6, 2, v5
	v_and_b32_e32 v5, 3, v5
	v_mul_u32_u24_e32 v6, 0x1000, v6
	v_lshl_add_u32 v6, v5, 7, v6
	v_add_u32_e32 v6, v6, v2
	global_load_dword v254, v6, s[98:99]

; __device__ __forceinline__ void xcd_barrier(const XcdBarrier& b, bool local = false) {
;     asm volatile("s_waitcnt vmcnt(0)" ::: "memory");
;     __syncthreads();
;     if (threadIdx.x == 0) {
; __global__ void __launch_bounds__(512, 2) fwd_megakernel(Args a) {
;     ...
;             pg8::Gemm g{hb1, (const bf16_t*)(ws + WS_WG + l * SZ_WO), DM, DM, DM, MTOK / 256, DM / 256, 0, lx, lr};
;             EpiGate E{hb1, (const bf16_t*)(ws + WS_PLE + l * SZ_ACT), hb0, ssq + (l + 1) * MTOK};
;             pg8::gemm_phase<EpiGate>(lds, g, E);
.LBB0_771:
	s_or_b64 exec, exec, s[40:41]
	s_and_b64 vcc, exec, s[76:77]
	s_cbranch_vccz .Lwu2_x
	v_readfirstlane_b32 s98, v188
	s_cmp_lt_u32 s98, 64
	s_cbranch_scc1 .Lwu2_x
	v_readlane_b32 s98, v251, 38
	v_readlane_b32 s99, v251, 43
	v_readlane_b32 vcc_lo, v251, 53
	v_mov_b32_e32 v2, 0x100000
	v_mov_b32_e32 v3, 0x800000
	s_nop 0
	v_mul_lo_u32 v2, v2, vcc_lo
	v_mul_lo_u32 v3, v3, s78
	v_add_u32_e32 v2, v2, v3
	v_subrev_u32_e32 v4, 64, v188
	v_add_u32_e32 v5, 0, v4
	v_min_u32_e32 v5, 0x3ff, v5
	v_lshrrev_b32_e32 v6, 2, v5
	v_and_b32_e32 v5, 3, v5
	v_mul_u32_u24_e32 v6, 0x1000, v6
	v_lshl_add_u32 v6, v5, 7, v6
	v_add_u32_e32 v6, v6, v2
	global_load_dword v254, v6, s[98:99]
	v_add_u32_e32 v5, 448, v4
	v_min_u32_e32 v5, 0x3ff, v5
	v_lshrrev_b32_e32 v6, 2, v5
	v_and_b32_e32 v5, 3, v5
	v_mul_u32_u24_e32 v6, 0x1000, v6
	v_lshl_add_u32 v6, v5, 7, v6
	v_add_u32_e32 v6, v6, v2
	global_load_dword v254, v6, s[98:99]
	v_add_u32_e32 v5, 896, v4
	v_min_u32_e32 v5, 0x3ff, v5
	v_lshrrev_b32_e32 v6, 2, v5
	v_and_b32_e32 v5, 3, v5
	v_mul_u32_u24_e32 v6, 0x1000, v6
	v_lshl_add_u32 v6, v5, 7, v6
	v_add_u32_e32 v6, v6, v2
	global_load_dword v254, v6, s[98:99]
